# v73 + fused ResidNorm epilogues (out-proj, FFN2): the four exchanged row-statistic loads issued together with counted waits instead of three serialized round trips
# speedup vs baseline: 1.0082x; 1.0059x over previous
.LBB0_117:
	s_or_b64 exec, exec, s[6:7]
	s_waitcnt vmcnt(0) lgkmcnt(0)
	s_barrier
	s_and_saveexec_b64 s[6:7], s[0:1]
	s_cbranch_execz .LBB0_119
	global_load_dword v160, v[162:163], off sc1
	global_load_dword v164, v[162:163], off offset:4 sc1
	global_load_dword v165, v[162:163], off offset:8 sc1
	global_load_dword v166, v[162:163], off offset:12 sc1
	v_readlane_b32 s0, v254, 4
	s_waitcnt vmcnt(3)
	v_add_f32_e32 v160, 0, v160
	s_waitcnt vmcnt(2)
	v_add_f32_e32 v160, v160, v164
	s_waitcnt vmcnt(1)
	v_add_f32_e32 v160, v160, v165
	s_waitcnt vmcnt(0)
	v_add_f32_e32 v160, v160, v166
	v_fmamk_f32 v160, v160, 0x3a800000, v237
	v_rsq_f32_e32 v160, v160
	v_lshl_add_u32 v162, v206, 2, s0
	ds_write_b32 v162, v160

.LBB0_662:
	s_or_b64 exec, exec, s[8:9]
	s_waitcnt vmcnt(0) lgkmcnt(0)
	s_barrier
	s_and_saveexec_b64 s[2:3], s[0:1]
	s_cbranch_execz .LBB0_664
	global_load_dword v160, v[162:163], off sc1
	global_load_dword v164, v[162:163], off offset:4 sc1
	global_load_dword v165, v[162:163], off offset:8 sc1
	global_load_dword v166, v[162:163], off offset:12 sc1
	v_readlane_b32 s0, v254, 4
	s_waitcnt vmcnt(3)
	v_add_f32_e32 v160, 0, v160
	s_waitcnt vmcnt(2)
	v_add_f32_e32 v160, v160, v164
	s_waitcnt vmcnt(1)
	v_add_f32_e32 v160, v160, v165
	s_waitcnt vmcnt(0)
	v_add_f32_e32 v160, v160, v166
	v_fmamk_f32 v160, v160, 0x3a800000, v237
	v_rsq_f32_e32 v160, v160
	v_lshl_add_u32 v162, v206, 2, s0
	ds_write_b32 v162, v160
